# branch-GEMM epilogue: gate loads of row group k+1 issued before the arithmetic of group k (software pipelining by one group, spare registers)
# speedup vs baseline: 1.0321x; 1.0072x over previous
; __device__ __forceinline__ u32x4 pack8(f32x4 v0, f32x4 v1) { u32x4 w; w.x = cvt_pk_bf16(v0[0], v0[1]); w.y = cvt_pk_bf16(v0[2], v0[3]); w.z = cvt_pk_bf16(v1[0], v1[1]); w.w = cvt_pk_bf16(v1[2], v1[3]); return w; }
; __device__ __forceinline__ f32x4 dq4u8(unsigned w) { return (f32x4){(float)(w & 0xffu), (float)((w >> 8) & 0xffu), (float)((w >> 16) & 0xffu), (float)(w >> 24)}; }
;     __device__ __forceinline__ void operator()(f32x4 (&acc)[2][2][4][2], const Unit& u, int wr, int wc, int fr, int fq) const {
;     ...
;             for (int q = 0; q < 2; ++q) { const int m = 2 * mp2 + q; const size_t row = (size_t)(row0 + ai * HALF + m * 16); const unsigned char* gp = (const unsigned char*)G + row * 3072 + col0;
; #pragma unroll
;                 for (int bj = 0; bj < 2; ++bj) { ga[q][bj] = *(const u32x2q*)(gp + n * 1024 + bj * HALF); gb[q][bj] = *(const u32x2q*)(gp + nn * 1024 + bj * HALF); } }
;             asm volatile("" : "+v"(ga[0][0]), "+v"(ga[0][1]), "+v"(ga[1][0]), "+v"(ga[1][1]), "+v"(gb[0][0]), "+v"(gb[0][1]), "+v"(gb[1][0]), "+v"(gb[1][1]));
; #pragma unroll
;             for (int q = 0; q < 2; ++q) { const int m = 2 * mp2 + q; const size_t row = (size_t)(row0 + ai * HALF + m * 16);
;                 if (n < 2) {
; #pragma unroll
;                     for (int bj = 0; bj < 2; ++bj) { const f32x4 d0 = dq4u8(gb[q][bj].x), d1 = dq4u8(gb[q][bj].y);
;                         const f32x4 r0 = dq4u8(ga[q][bj].x) * (f32x4){__builtin_amdgcn_rcpf(d0[0]), __builtin_amdgcn_rcpf(d0[1]), __builtin_amdgcn_rcpf(d0[2]), __builtin_amdgcn_rcpf(d0[3])};
;                         const f32x4 r1 = dq4u8(ga[q][bj].y) * (f32x4){__builtin_amdgcn_rcpf(d1[0]), __builtin_amdgcn_rcpf(d1[1]), __builtin_amdgcn_rcpf(d1[2]), __builtin_amdgcn_rcpf(d1[3])};
;                         acc[ai][bj][m][0] *= r0; acc[ai][bj][m][1] *= r1; }
;                 } else { bf16_t* mp = MG + row * 1024 + col0;
; #pragma unroll
;                     for (int bj = 0; bj < 2; ++bj) *(u32x4*)(mp + bj * HALF) = pack8(dq4u8(ga[q][bj].x) * (acc[ai][bj][m][0] * (1.0f / 255.0f)), dq4u8(ga[q][bj].y) * (acc[ai][bj][m][1] * (1.0f / 255.0f))); } }
.LBB0_1041:
	s_lshl_b32 s0, s26, 8
	s_ashr_i32 s6, s26, 2
	s_and_b32 s0, s0, 0x300
	s_cmp_gt_i32 s6, 1
	s_cselect_b64 s[28:29], -1, 0
	s_cmp_lt_i32 s6, 2
	v_or_b32_e32 v0, s0, v180
	s_cselect_b64 s[0:1], -1, 0
	s_cmp_lg_u64 s[0:1], 0
	s_addc_u32 s0, s6, 0
	v_lshl_add_u32 v2, s24, 8, v178
	s_lshl_b32 s24, s6, 10
	s_lshl_b32 s26, s0, 10
	v_lshl_add_u64 v[144:145], s[12:13], 0, v[0:1]
	s_ashr_i32 s25, s24, 31
	s_ashr_i32 s27, s26, 31
	v_mad_i64_i32 v[146:147], s[0:1], v2, s56, v[144:145]
	v_lshl_add_u64 v[148:149], v[146:147], 0, s[24:25]
	v_lshl_add_u64 v[146:147], v[146:147], 0, s[26:27]
	v_or_b32_e32 v150, 16, v2
	global_load_dwordx2 v[156:157], v[148:149], off
	global_load_dwordx2 v[170:171], v[146:147], off
	global_load_dwordx2 v[158:159], v[146:147], off offset:128
	global_load_dwordx2 v[176:177], v[148:149], off offset:128
	v_mad_i64_i32 v[146:147], s[0:1], v150, s56, v[144:145]
	v_lshl_add_u64 v[152:153], v[146:147], 0, s[24:25]
	v_lshl_add_u64 v[146:147], v[146:147], 0, s[26:27]
	global_load_dwordx2 v[154:155], v[152:153], off
	global_load_dwordx2 v[148:149], v[146:147], off
	s_nop 0
	global_load_dwordx2 v[146:147], v[146:147], off offset:128
	s_nop 0
	global_load_dwordx2 v[152:153], v[152:153], off offset:128
	s_mov_b64 s[6:7], -1
	v_ashrrev_i32_e32 v3, 31, v2
	v_lshlrev_b32_e32 v0, 1, v0
	s_and_b64 vcc, exec, s[28:29]
	s_waitcnt vmcnt(0)
	v_add_u32_e32 v217, 0x20, v2
	v_mad_i64_i32 v[252:253], s[62:63], v217, s56, v[144:145]
	v_lshl_add_u64 v[252:253], v[252:253], 0, s[24:25]
	global_load_dwordx2 v[192:193], v[252:253], off
	global_load_dwordx2 v[198:199], v[252:253], off offset:128
	v_mad_i64_i32 v[252:253], s[62:63], v217, s56, v[144:145]
	v_lshl_add_u64 v[252:253], v[252:253], 0, s[26:27]
	global_load_dwordx2 v[194:195], v[252:253], off
	global_load_dwordx2 v[196:197], v[252:253], off offset:128
	v_add_u32_e32 v217, 0x30, v2
	v_mad_i64_i32 v[252:253], s[62:63], v217, s56, v[144:145]
	v_lshl_add_u64 v[252:253], v[252:253], 0, s[24:25]
	global_load_dwordx2 v[200:201], v[252:253], off
	global_load_dwordx2 v[206:207], v[252:253], off offset:128
	v_mad_i64_i32 v[252:253], s[62:63], v217, s56, v[144:145]
	v_lshl_add_u64 v[252:253], v[252:253], 0, s[26:27]
	global_load_dwordx2 v[202:203], v[252:253], off
	global_load_dwordx2 v[204:205], v[252:253], off offset:128
	s_nop 0
	v_cvt_f32_ubyte1_e32 v173, v156
	v_cvt_f32_ubyte0_e32 v172, v156
	v_cvt_f32_ubyte3_e32 v175, v156
	v_cvt_f32_ubyte2_e32 v174, v156
	v_cvt_f32_ubyte1_e32 v169, v157
	v_cvt_f32_ubyte0_e32 v168, v157
	v_cvt_f32_ubyte3_e32 v167, v157
	v_cvt_f32_ubyte2_e32 v166, v157
	v_cvt_f32_ubyte1_e32 v163, v176
	v_cvt_f32_ubyte0_e32 v162, v176
	v_cvt_f32_ubyte3_e32 v165, v176
	v_cvt_f32_ubyte2_e32 v164, v176
	v_cvt_f32_ubyte1_e32 v161, v177
	v_cvt_f32_ubyte0_e32 v160, v177
	v_cvt_f32_ubyte3_e32 v157, v177
	v_cvt_f32_ubyte2_e32 v156, v177
	s_cbranch_vccz .LBB0_1043
	s_mov_b32 s0, 0x3b808081
	v_pk_mul_f32 v[182:183], v[130:131], s[0:1] op_sel_hi:[1,0]
	v_pk_mul_f32 v[184:185], v[128:129], s[0:1] op_sel_hi:[1,0]
	v_lshlrev_b64 v[176:177], 11, v[2:3]
	v_pk_mul_f32 v[186:187], v[182:183], v[174:175]
	v_pk_mul_f32 v[182:183], v[184:185], v[172:173]
	v_pk_mul_f32 v[184:185], v[126:127], s[0:1] op_sel_hi:[1,0]
	v_pk_mul_f32 v[188:189], v[124:125], s[0:1] op_sel_hi:[1,0]
	v_lshl_add_u64 v[176:177], s[10:11], 0, v[176:177]
	v_pk_mul_f32 v[190:191], v[184:185], v[166:167]
	v_pk_mul_f32 v[184:185], v[188:189], v[168:169]
	v_lshl_add_u64 v[176:177], v[176:177], 0, v[0:1]
	v_cvt_pk_bf16_f32 v182, v182, v183
	v_cvt_pk_bf16_f32 v183, v186, v187
	v_cvt_pk_bf16_f32 v184, v184, v185
	v_cvt_pk_bf16_f32 v185, v190, v191
	global_store_dwordx4 v[176:177], v[182:185], off
	v_pk_mul_f32 v[188:189], v[92:93], s[0:1] op_sel_hi:[1,0]
	s_mov_b64 s[6:7], 0
	v_pk_mul_f32 v[182:183], v[98:99], s[0:1] op_sel_hi:[1,0]
	v_pk_mul_f32 v[184:185], v[96:97], s[0:1] op_sel_hi:[1,0]
	v_pk_mul_f32 v[186:187], v[182:183], v[164:165]
	v_pk_mul_f32 v[182:183], v[184:185], v[162:163]
	v_pk_mul_f32 v[184:185], v[94:95], s[0:1] op_sel_hi:[1,0]
	v_cvt_pk_bf16_f32 v182, v182, v183
	v_pk_mul_f32 v[190:191], v[184:185], v[156:157]
	v_pk_mul_f32 v[184:185], v[188:189], v[160:161]
	v_cvt_pk_bf16_f32 v183, v186, v187
	v_cvt_pk_bf16_f32 v184, v184, v185
	v_cvt_pk_bf16_f32 v185, v190, v191
	global_store_dwordx4 v[176:177], v[182:185], off offset:256

; __device__ __forceinline__ u32x4 pack8(f32x4 v0, f32x4 v1) { u32x4 w; w.x = cvt_pk_bf16(v0[0], v0[1]); w.y = cvt_pk_bf16(v0[2], v0[3]); w.z = cvt_pk_bf16(v1[0], v1[1]); w.w = cvt_pk_bf16(v1[2], v1[3]); return w; }
; __device__ __forceinline__ f32x4 dq4u8(unsigned w) { return (f32x4){(float)(w & 0xffu), (float)((w >> 8) & 0xffu), (float)((w >> 16) & 0xffu), (float)(w >> 24)}; }
;     __device__ __forceinline__ void operator()(f32x4 (&acc)[2][2][4][2], const Unit& u, int wr, int wc, int fr, int fq) const {
;     ...
;             for (int q = 0; q < 2; ++q) { const int m = 2 * mp2 + q; const size_t row = (size_t)(row0 + ai * HALF + m * 16); const unsigned char* gp = (const unsigned char*)G + row * 3072 + col0;
; #pragma unroll
;                 for (int bj = 0; bj < 2; ++bj) { ga[q][bj] = *(const u32x2q*)(gp + n * 1024 + bj * HALF); gb[q][bj] = *(const u32x2q*)(gp + nn * 1024 + bj * HALF); } }
;             asm volatile("" : "+v"(ga[0][0]), "+v"(ga[0][1]), "+v"(ga[1][0]), "+v"(ga[1][1]), "+v"(gb[0][0]), "+v"(gb[0][1]), "+v"(gb[1][0]), "+v"(gb[1][1]));
; #pragma unroll
;             for (int q = 0; q < 2; ++q) { const int m = 2 * mp2 + q; const size_t row = (size_t)(row0 + ai * HALF + m * 16);
;                 if (n < 2) {
; #pragma unroll
;                     for (int bj = 0; bj < 2; ++bj) { const f32x4 d0 = dq4u8(gb[q][bj].x), d1 = dq4u8(gb[q][bj].y);
;                         const f32x4 r0 = dq4u8(ga[q][bj].x) * (f32x4){__builtin_amdgcn_rcpf(d0[0]), __builtin_amdgcn_rcpf(d0[1]), __builtin_amdgcn_rcpf(d0[2]), __builtin_amdgcn_rcpf(d0[3])};
;                         const f32x4 r1 = dq4u8(ga[q][bj].y) * (f32x4){__builtin_amdgcn_rcpf(d1[0]), __builtin_amdgcn_rcpf(d1[1]), __builtin_amdgcn_rcpf(d1[2]), __builtin_amdgcn_rcpf(d1[3])};
;                         acc[ai][bj][m][0] *= r0; acc[ai][bj][m][1] *= r1; }
;                 } else { bf16_t* mp = MG + row * 1024 + col0;
; #pragma unroll
;                     for (int bj = 0; bj < 2; ++bj) *(u32x4*)(mp + bj * HALF) = pack8(dq4u8(ga[q][bj].x) * (acc[ai][bj][m][0] * (1.0f / 255.0f)), dq4u8(ga[q][bj].y) * (acc[ai][bj][m][1] * (1.0f / 255.0f))); } }
.LBB0_1049:
	v_or_b32_e32 v176, 32, v2
	v_mad_i64_i32 v[146:147], s[0:1], v176, s56, v[144:145]
	v_lshl_add_u64 v[148:149], v[146:147], 0, s[24:25]
	v_lshl_add_u64 v[146:147], v[146:147], 0, s[26:27]
	v_or_b32_e32 v150, 48, v2
	s_waitcnt vmcnt(0)
	v_mov_b32_e32 v156, v192
	v_mov_b32_e32 v157, v193
	v_mov_b32_e32 v170, v194
	v_mov_b32_e32 v171, v195
	v_mov_b32_e32 v160, v196
	v_mov_b32_e32 v161, v197
	v_mov_b32_e32 v182, v198
	v_mov_b32_e32 v183, v199
	v_mad_i64_i32 v[146:147], s[0:1], v150, s56, v[144:145]
	v_lshl_add_u64 v[152:153], v[146:147], 0, s[24:25]
	v_lshl_add_u64 v[146:147], v[146:147], 0, s[26:27]
	v_mov_b32_e32 v154, v200
	v_mov_b32_e32 v155, v201
	v_mov_b32_e32 v148, v202
	v_mov_b32_e32 v149, v203
	s_nop 0
	v_mov_b32_e32 v146, v204
	v_mov_b32_e32 v147, v205
	s_nop 0
	v_mov_b32_e32 v152, v206
	v_mov_b32_e32 v153, v207
	s_mov_b64 s[28:29], -1
	s_and_b64 vcc, exec, s[6:7]
	s_waitcnt vmcnt(0)
	v_add_u32_e32 v217, 0x80, v2
	v_mad_i64_i32 v[252:253], s[62:63], v217, s56, v[144:145]
	v_lshl_add_u64 v[252:253], v[252:253], 0, s[24:25]
	global_load_dwordx2 v[208:209], v[252:253], off
	global_load_dwordx2 v[214:215], v[252:253], off offset:128
	v_mad_i64_i32 v[252:253], s[62:63], v217, s56, v[144:145]
	v_lshl_add_u64 v[252:253], v[252:253], 0, s[26:27]
	global_load_dwordx2 v[210:211], v[252:253], off
	global_load_dwordx2 v[212:213], v[252:253], off offset:128
	v_add_u32_e32 v217, 0x90, v2
	v_mad_i64_i32 v[252:253], s[62:63], v217, s56, v[144:145]
	v_lshl_add_u64 v[252:253], v[252:253], 0, s[24:25]
	global_load_dwordx2 v[220:221], v[252:253], off
	global_load_dwordx2 v[226:227], v[252:253], off offset:128
	v_mad_i64_i32 v[252:253], s[62:63], v217, s56, v[144:145]
	v_lshl_add_u64 v[252:253], v[252:253], 0, s[26:27]
	global_load_dwordx2 v[222:223], v[252:253], off
	global_load_dwordx2 v[224:225], v[252:253], off offset:128
	s_nop 0
	v_cvt_f32_ubyte1_e32 v173, v156
	v_cvt_f32_ubyte0_e32 v172, v156
	v_cvt_f32_ubyte3_e32 v175, v156
	v_cvt_f32_ubyte2_e32 v174, v156
	v_cvt_f32_ubyte1_e32 v169, v157
	v_cvt_f32_ubyte0_e32 v168, v157
	v_cvt_f32_ubyte3_e32 v167, v157
	v_cvt_f32_ubyte2_e32 v166, v157
	v_cvt_f32_ubyte1_e32 v163, v182
	v_cvt_f32_ubyte0_e32 v162, v182
	v_cvt_f32_ubyte3_e32 v165, v182
	v_cvt_f32_ubyte2_e32 v164, v182
	v_cvt_f32_ubyte1_e32 v159, v183
	v_cvt_f32_ubyte0_e32 v158, v183
	v_cvt_f32_ubyte3_e32 v157, v183
	v_cvt_f32_ubyte2_e32 v156, v183
	s_cbranch_vccnz .LBB0_1051
	s_mov_b32 s0, 0x3b808081
	v_ashrrev_i32_e32 v177, 31, v176
	v_pk_mul_f32 v[182:183], v[114:115], s[0:1] op_sel_hi:[1,0]
	v_pk_mul_f32 v[184:185], v[112:113], s[0:1] op_sel_hi:[1,0]
	v_lshlrev_b64 v[176:177], 11, v[176:177]
	v_pk_mul_f32 v[186:187], v[182:183], v[174:175]
	v_pk_mul_f32 v[182:183], v[184:185], v[172:173]
	v_pk_mul_f32 v[184:185], v[110:111], s[0:1] op_sel_hi:[1,0]
	v_pk_mul_f32 v[188:189], v[108:109], s[0:1] op_sel_hi:[1,0]
	v_lshl_add_u64 v[176:177], s[10:11], 0, v[176:177]
	v_pk_mul_f32 v[190:191], v[184:185], v[166:167]
	v_pk_mul_f32 v[184:185], v[188:189], v[168:169]
	v_lshl_add_u64 v[176:177], v[176:177], 0, v[0:1]
	v_cvt_pk_bf16_f32 v182, v182, v183
	v_cvt_pk_bf16_f32 v183, v186, v187
	v_cvt_pk_bf16_f32 v184, v184, v185
	v_cvt_pk_bf16_f32 v185, v190, v191
	global_store_dwordx4 v[176:177], v[182:185], off
	v_pk_mul_f32 v[188:189], v[76:77], s[0:1] op_sel_hi:[1,0]
	s_mov_b64 s[28:29], 0
	v_pk_mul_f32 v[182:183], v[82:83], s[0:1] op_sel_hi:[1,0]
	v_pk_mul_f32 v[184:185], v[80:81], s[0:1] op_sel_hi:[1,0]
	v_pk_mul_f32 v[186:187], v[182:183], v[164:165]
	v_pk_mul_f32 v[182:183], v[184:185], v[162:163]
	v_pk_mul_f32 v[184:185], v[78:79], s[0:1] op_sel_hi:[1,0]
	v_cvt_pk_bf16_f32 v182, v182, v183
	v_pk_mul_f32 v[190:191], v[184:185], v[156:157]
	v_pk_mul_f32 v[184:185], v[188:189], v[158:159]
	v_cvt_pk_bf16_f32 v183, v186, v187
	v_cvt_pk_bf16_f32 v184, v184, v185
	v_cvt_pk_bf16_f32 v185, v190, v191
	global_store_dwordx4 v[176:177], v[182:185], off offset:256

; __device__ __forceinline__ u32x4 pack8(f32x4 v0, f32x4 v1) { u32x4 w; w.x = cvt_pk_bf16(v0[0], v0[1]); w.y = cvt_pk_bf16(v0[2], v0[3]); w.z = cvt_pk_bf16(v1[0], v1[1]); w.w = cvt_pk_bf16(v1[2], v1[3]); return w; }
; __device__ __forceinline__ f32x4 dq4u8(unsigned w) { return (f32x4){(float)(w & 0xffu), (float)((w >> 8) & 0xffu), (float)((w >> 16) & 0xffu), (float)(w >> 24)}; }
;     __device__ __forceinline__ void operator()(f32x4 (&acc)[2][2][4][2], const Unit& u, int wr, int wc, int fr, int fq) const {
;     ...
;             for (int q = 0; q < 2; ++q) { const int m = 2 * mp2 + q; const size_t row = (size_t)(row0 + ai * HALF + m * 16); const unsigned char* gp = (const unsigned char*)G + row * 3072 + col0;
; #pragma unroll
;                 for (int bj = 0; bj < 2; ++bj) { ga[q][bj] = *(const u32x2q*)(gp + n * 1024 + bj * HALF); gb[q][bj] = *(const u32x2q*)(gp + nn * 1024 + bj * HALF); } }
;             asm volatile("" : "+v"(ga[0][0]), "+v"(ga[0][1]), "+v"(ga[1][0]), "+v"(ga[1][1]), "+v"(gb[0][0]), "+v"(gb[0][1]), "+v"(gb[1][0]), "+v"(gb[1][1]));
; #pragma unroll
;             for (int q = 0; q < 2; ++q) { const int m = 2 * mp2 + q; const size_t row = (size_t)(row0 + ai * HALF + m * 16);
;                 if (n < 2) {
; #pragma unroll
;                     for (int bj = 0; bj < 2; ++bj) { const f32x4 d0 = dq4u8(gb[q][bj].x), d1 = dq4u8(gb[q][bj].y);
;                         const f32x4 r0 = dq4u8(ga[q][bj].x) * (f32x4){__builtin_amdgcn_rcpf(d0[0]), __builtin_amdgcn_rcpf(d0[1]), __builtin_amdgcn_rcpf(d0[2]), __builtin_amdgcn_rcpf(d0[3])};
;                         const f32x4 r1 = dq4u8(ga[q][bj].y) * (f32x4){__builtin_amdgcn_rcpf(d1[0]), __builtin_amdgcn_rcpf(d1[1]), __builtin_amdgcn_rcpf(d1[2]), __builtin_amdgcn_rcpf(d1[3])};
;                         acc[ai][bj][m][0] *= r0; acc[ai][bj][m][1] *= r1; }
;                 } else { bf16_t* mp = MG + row * 1024 + col0;
; #pragma unroll
;                     for (int bj = 0; bj < 2; ++bj) *(u32x4*)(mp + bj * HALF) = pack8(dq4u8(ga[q][bj].x) * (acc[ai][bj][m][0] * (1.0f / 255.0f)), dq4u8(ga[q][bj].y) * (acc[ai][bj][m][1] * (1.0f / 255.0f))); } }
.LBB0_1057:
	v_add_u32_e32 v176, 0x80, v2
	v_mad_i64_i32 v[146:147], s[0:1], v176, s56, v[144:145]
	v_lshl_add_u64 v[148:149], v[146:147], 0, s[24:25]
	v_lshl_add_u64 v[146:147], v[146:147], 0, s[26:27]
	v_add_u32_e32 v150, 0x90, v2
	s_waitcnt vmcnt(0)
	v_mov_b32_e32 v156, v208
	v_mov_b32_e32 v157, v209
	v_mov_b32_e32 v170, v210
	v_mov_b32_e32 v171, v211
	v_mov_b32_e32 v160, v212
	v_mov_b32_e32 v161, v213
	v_mov_b32_e32 v182, v214
	v_mov_b32_e32 v183, v215
	v_mad_i64_i32 v[146:147], s[0:1], v150, s56, v[144:145]
	v_lshl_add_u64 v[152:153], v[146:147], 0, s[24:25]
	v_lshl_add_u64 v[146:147], v[146:147], 0, s[26:27]
	v_mov_b32_e32 v154, v220
	v_mov_b32_e32 v155, v221
	v_mov_b32_e32 v148, v222
	v_mov_b32_e32 v149, v223
	s_nop 0
	v_mov_b32_e32 v146, v224
	v_mov_b32_e32 v147, v225
	s_nop 0
	v_mov_b32_e32 v152, v226
	v_mov_b32_e32 v153, v227
	s_mov_b64 s[28:29], -1
	s_and_b64 vcc, exec, s[6:7]
	s_waitcnt vmcnt(0)
	v_add_u32_e32 v217, 0xa0, v2
	v_mad_i64_i32 v[252:253], s[62:63], v217, s56, v[144:145]
	v_lshl_add_u64 v[252:253], v[252:253], 0, s[24:25]
	global_load_dwordx2 v[228:229], v[252:253], off
	global_load_dwordx2 v[236:237], v[252:253], off offset:128
	v_mad_i64_i32 v[252:253], s[62:63], v217, s56, v[144:145]
	v_lshl_add_u64 v[252:253], v[252:253], 0, s[26:27]
	global_load_dwordx2 v[230:231], v[252:253], off
	global_load_dwordx2 v[234:235], v[252:253], off offset:128
	v_add_u32_e32 v217, 0xb0, v2
	v_mad_i64_i32 v[252:253], s[62:63], v217, s56, v[144:145]
	v_lshl_add_u64 v[252:253], v[252:253], 0, s[24:25]
	global_load_dwordx2 v[244:245], v[252:253], off
	global_load_dwordx2 v[250:251], v[252:253], off offset:128
	v_mad_i64_i32 v[252:253], s[62:63], v217, s56, v[144:145]
	v_lshl_add_u64 v[252:253], v[252:253], 0, s[26:27]
	global_load_dwordx2 v[246:247], v[252:253], off
	global_load_dwordx2 v[248:249], v[252:253], off offset:128
	s_nop 0
	v_cvt_f32_ubyte1_e32 v173, v156
	v_cvt_f32_ubyte0_e32 v172, v156
	v_cvt_f32_ubyte3_e32 v175, v156
	v_cvt_f32_ubyte2_e32 v174, v156
	v_cvt_f32_ubyte1_e32 v169, v157
	v_cvt_f32_ubyte0_e32 v168, v157
	v_cvt_f32_ubyte3_e32 v167, v157
	v_cvt_f32_ubyte2_e32 v166, v157
	v_cvt_f32_ubyte1_e32 v163, v182
	v_cvt_f32_ubyte0_e32 v162, v182
	v_cvt_f32_ubyte3_e32 v165, v182
	v_cvt_f32_ubyte2_e32 v164, v182
	v_cvt_f32_ubyte1_e32 v159, v183
	v_cvt_f32_ubyte0_e32 v158, v183
	v_cvt_f32_ubyte3_e32 v157, v183
	v_cvt_f32_ubyte2_e32 v156, v183
	s_cbranch_vccnz .LBB0_1059
	s_mov_b32 s0, 0x3b808081
	v_ashrrev_i32_e32 v177, 31, v176
	v_pk_mul_f32 v[182:183], v[66:67], s[0:1] op_sel_hi:[1,0]
	v_pk_mul_f32 v[184:185], v[64:65], s[0:1] op_sel_hi:[1,0]
	v_lshlrev_b64 v[176:177], 11, v[176:177]
	v_pk_mul_f32 v[186:187], v[182:183], v[174:175]
	v_pk_mul_f32 v[182:183], v[184:185], v[172:173]
	v_pk_mul_f32 v[184:185], v[62:63], s[0:1] op_sel_hi:[1,0]
	v_pk_mul_f32 v[188:189], v[60:61], s[0:1] op_sel_hi:[1,0]
	v_lshl_add_u64 v[176:177], s[10:11], 0, v[176:177]
	v_pk_mul_f32 v[190:191], v[184:185], v[166:167]
	v_pk_mul_f32 v[184:185], v[188:189], v[168:169]
	v_lshl_add_u64 v[176:177], v[176:177], 0, v[0:1]
	v_cvt_pk_bf16_f32 v182, v182, v183
	v_cvt_pk_bf16_f32 v183, v186, v187
	v_cvt_pk_bf16_f32 v184, v184, v185
	v_cvt_pk_bf16_f32 v185, v190, v191
	global_store_dwordx4 v[176:177], v[182:185], off
	v_pk_mul_f32 v[188:189], v[28:29], s[0:1] op_sel_hi:[1,0]
	s_mov_b64 s[28:29], 0
	v_pk_mul_f32 v[182:183], v[34:35], s[0:1] op_sel_hi:[1,0]
	v_pk_mul_f32 v[184:185], v[32:33], s[0:1] op_sel_hi:[1,0]
	v_pk_mul_f32 v[186:187], v[182:183], v[164:165]
	v_pk_mul_f32 v[182:183], v[184:185], v[162:163]
	v_pk_mul_f32 v[184:185], v[30:31], s[0:1] op_sel_hi:[1,0]
	v_cvt_pk_bf16_f32 v182, v182, v183
	v_pk_mul_f32 v[190:191], v[184:185], v[156:157]
	v_pk_mul_f32 v[184:185], v[188:189], v[158:159]
	v_cvt_pk_bf16_f32 v183, v186, v187
	v_cvt_pk_bf16_f32 v184, v184, v185
	v_cvt_pk_bf16_f32 v185, v190, v191
	global_store_dwordx4 v[176:177], v[182:185], off offset:256

; __device__ __forceinline__ u32x4 pack8(f32x4 v0, f32x4 v1) { u32x4 w; w.x = cvt_pk_bf16(v0[0], v0[1]); w.y = cvt_pk_bf16(v0[2], v0[3]); w.z = cvt_pk_bf16(v1[0], v1[1]); w.w = cvt_pk_bf16(v1[2], v1[3]); return w; }
; __device__ __forceinline__ f32x4 dq4u8(unsigned w) { return (f32x4){(float)(w & 0xffu), (float)((w >> 8) & 0xffu), (float)((w >> 16) & 0xffu), (float)(w >> 24)}; }
;     __device__ __forceinline__ void operator()(f32x4 (&acc)[2][2][4][2], const Unit& u, int wr, int wc, int fr, int fq) const {
;     ...
;             for (int q = 0; q < 2; ++q) { const int m = 2 * mp2 + q; const size_t row = (size_t)(row0 + ai * HALF + m * 16); const unsigned char* gp = (const unsigned char*)G + row * 3072 + col0;
; #pragma unroll
;                 for (int bj = 0; bj < 2; ++bj) { ga[q][bj] = *(const u32x2q*)(gp + n * 1024 + bj * HALF); gb[q][bj] = *(const u32x2q*)(gp + nn * 1024 + bj * HALF); } }
;             asm volatile("" : "+v"(ga[0][0]), "+v"(ga[0][1]), "+v"(ga[1][0]), "+v"(ga[1][1]), "+v"(gb[0][0]), "+v"(gb[0][1]), "+v"(gb[1][0]), "+v"(gb[1][1]));
; #pragma unroll
;             for (int q = 0; q < 2; ++q) { const int m = 2 * mp2 + q; const size_t row = (size_t)(row0 + ai * HALF + m * 16);
;                 if (n < 2) {
; #pragma unroll
;                     for (int bj = 0; bj < 2; ++bj) { const f32x4 d0 = dq4u8(gb[q][bj].x), d1 = dq4u8(gb[q][bj].y);
;                         const f32x4 r0 = dq4u8(ga[q][bj].x) * (f32x4){__builtin_amdgcn_rcpf(d0[0]), __builtin_amdgcn_rcpf(d0[1]), __builtin_amdgcn_rcpf(d0[2]), __builtin_amdgcn_rcpf(d0[3])};
;                         const f32x4 r1 = dq4u8(ga[q][bj].y) * (f32x4){__builtin_amdgcn_rcpf(d1[0]), __builtin_amdgcn_rcpf(d1[1]), __builtin_amdgcn_rcpf(d1[2]), __builtin_amdgcn_rcpf(d1[3])};
;                         acc[ai][bj][m][0] *= r0; acc[ai][bj][m][1] *= r1; }
;                 } else { bf16_t* mp = MG + row * 1024 + col0;
; #pragma unroll
;                     for (int bj = 0; bj < 2; ++bj) *(u32x4*)(mp + bj * HALF) = pack8(dq4u8(ga[q][bj].x) * (acc[ai][bj][m][0] * (1.0f / 255.0f)), dq4u8(ga[q][bj].y) * (acc[ai][bj][m][1] * (1.0f / 255.0f))); } }
.LBB0_1065:
	v_add_u32_e32 v172, 0xa0, v2
	v_mad_i64_i32 v[146:147], s[0:1], v172, s56, v[144:145]
	v_lshl_add_u64 v[148:149], v[146:147], 0, s[24:25]
	v_lshl_add_u64 v[146:147], v[146:147], 0, s[26:27]
	s_waitcnt vmcnt(0)
	v_mov_b32_e32 v152, v228
	v_mov_b32_e32 v153, v229
	v_mov_b32_e32 v166, v230
	v_mov_b32_e32 v167, v231
	v_mov_b32_e32 v156, v234
	v_mov_b32_e32 v157, v235
	v_mov_b32_e32 v174, v236
	v_mov_b32_e32 v175, v237
	v_add_u32_e32 v146, 0xb0, v2
	v_mad_i64_i32 v[2:3], s[0:1], v146, s56, v[144:145]
	v_lshl_add_u64 v[148:149], v[2:3], 0, s[24:25]
	v_lshl_add_u64 v[2:3], v[2:3], 0, s[26:27]
	v_mov_b32_e32 v150, v244
	v_mov_b32_e32 v151, v245
	v_mov_b32_e32 v144, v246
	v_mov_b32_e32 v145, v247
	s_nop 0
	v_mov_b32_e32 v2, v248
	v_mov_b32_e32 v3, v249
	s_nop 0
	v_mov_b32_e32 v148, v250
	v_mov_b32_e32 v149, v251
	s_mov_b64 s[24:25], -1
	s_and_b64 vcc, exec, s[6:7]
	s_waitcnt vmcnt(0)
	s_nop 0
	v_cvt_f32_ubyte1_e32 v169, v152
	v_cvt_f32_ubyte0_e32 v168, v152
	v_cvt_f32_ubyte3_e32 v171, v152
	v_cvt_f32_ubyte2_e32 v170, v152
	v_cvt_f32_ubyte1_e32 v165, v153
	v_cvt_f32_ubyte0_e32 v164, v153
	v_cvt_f32_ubyte3_e32 v163, v153
	v_cvt_f32_ubyte2_e32 v162, v153
	v_cvt_f32_ubyte1_e32 v159, v174
	v_cvt_f32_ubyte0_e32 v158, v174
	v_cvt_f32_ubyte3_e32 v161, v174
	v_cvt_f32_ubyte2_e32 v160, v174
	v_cvt_f32_ubyte1_e32 v155, v175
	v_cvt_f32_ubyte0_e32 v154, v175
	v_cvt_f32_ubyte3_e32 v153, v175
	v_cvt_f32_ubyte2_e32 v152, v175
	s_cbranch_vccnz .LBB0_1067
	v_ashrrev_i32_e32 v173, 31, v172
	v_lshlrev_b64 v[172:173], 11, v[172:173]
	v_lshl_add_u64 v[172:173], s[10:11], 0, v[172:173]
	s_mov_b32 s0, 0x3b808081
	v_lshl_add_u64 v[176:177], v[172:173], 0, v[0:1]
	v_pk_mul_f32 v[172:173], v[50:51], s[0:1] op_sel_hi:[1,0]
	v_pk_mul_f32 v[174:175], v[48:49], s[0:1] op_sel_hi:[1,0]
	v_pk_mul_f32 v[182:183], v[172:173], v[170:171]
	v_pk_mul_f32 v[172:173], v[174:175], v[168:169]
	v_pk_mul_f32 v[174:175], v[46:47], s[0:1] op_sel_hi:[1,0]
	v_pk_mul_f32 v[184:185], v[44:45], s[0:1] op_sel_hi:[1,0]
	v_pk_mul_f32 v[186:187], v[174:175], v[162:163]
	v_pk_mul_f32 v[174:175], v[184:185], v[164:165]
	v_cvt_pk_bf16_f32 v172, v172, v173
	v_cvt_pk_bf16_f32 v173, v182, v183
	v_cvt_pk_bf16_f32 v174, v174, v175
	v_cvt_pk_bf16_f32 v175, v186, v187
	global_store_dwordx4 v[176:177], v[172:175], off
	v_pk_mul_f32 v[184:185], v[12:13], s[0:1] op_sel_hi:[1,0]
	s_mov_b64 s[24:25], 0
	v_pk_mul_f32 v[172:173], v[18:19], s[0:1] op_sel_hi:[1,0]
	v_pk_mul_f32 v[174:175], v[16:17], s[0:1] op_sel_hi:[1,0]
	v_pk_mul_f32 v[182:183], v[172:173], v[160:161]
	v_pk_mul_f32 v[172:173], v[174:175], v[158:159]
	v_pk_mul_f32 v[174:175], v[14:15], s[0:1] op_sel_hi:[1,0]
	v_cvt_pk_bf16_f32 v172, v172, v173
	v_pk_mul_f32 v[186:187], v[174:175], v[152:153]
	v_pk_mul_f32 v[174:175], v[184:185], v[154:155]
	v_cvt_pk_bf16_f32 v173, v182, v183
	v_cvt_pk_bf16_f32 v174, v174, v175
	v_cvt_pk_bf16_f32 v175, v186, v187
	global_store_dwordx4 v[176:177], v[172:175], off offset:256
